# as v67 with the conversion slices' LDS operations paced (8 wait states after every second ds_write and every ds_read2)
# speedup vs baseline: 1.0067x; 1.0042x over previous
; #define GAS __attribute__((address_space(1)))
; #define LAS __attribute__((address_space(3)))
; #define LDS_WAIT() asm volatile("s_waitcnt lgkmcnt(0)" ::: "memory")
; __device__ __forceinline__ unsigned pk2(float lo, float hi) { unsigned r; asm("v_cvt_pk_bf16_f32 %0, %1, %2" : "=v"(r) : "v"(lo), "v"(hi)); return r; }
; __device__ __forceinline__ void conv_proc(f32x4 (&v)[2][8], const float* gain, int K, int Kp, int Np, int ilv, bf16* WT, LAS float* scr, int item, int lane) {
;     ...
;         for (int i = 0; i < 8; ++i) { LAS float* d = scr + (8 * i + kr) * 33 + 4 * n4; d[0] = v[hf][i][0]; d[1] = v[hf][i][1]; d[2] = v[hf][i][2]; d[3] = v[hf][i][3]; }
;         LDS_WAIT(); asm volatile("" ::: "memory");
; #pragma unroll
;         for (int j = 0; j < 4; ++j) { const int nn = (lane >> 3) + 8 * j; const LAS float* sp = scr + (8 * c) * 33 + nn;
;             v4u o; o.x = pk2(sp[0 * 33], sp[1 * 33]); o.y = pk2(sp[2 * 33], sp[3 * 33]); o.z = pk2(sp[4 * 33], sp[5 * 33]); o.w = pk2(sp[6 * 33], sp[7 * 33]);
;             __builtin_nontemporal_store(o, (GAS v4u*)(WT + (size_t)(d0 + 32 * hf + nn) * Kp + k0 + 8 * c)); }
.Lcsap_nogain:
	ds_write_b32 v238, v188 offset:0
	ds_write_b32 v238, v189 offset:4
	s_nop 7
	ds_write_b32 v238, v190 offset:8
	ds_write_b32 v238, v191 offset:12
	s_nop 7
	ds_write_b32 v238, v192 offset:1056
	ds_write_b32 v238, v193 offset:1060
	s_nop 7
	ds_write_b32 v238, v194 offset:1064
	ds_write_b32 v238, v195 offset:1068
	s_nop 7
	ds_write_b32 v238, v196 offset:2112
	ds_write_b32 v238, v197 offset:2116
	s_nop 7
	ds_write_b32 v238, v198 offset:2120
	ds_write_b32 v238, v199 offset:2124
	s_nop 7
	ds_write_b32 v238, v200 offset:3168
	ds_write_b32 v238, v201 offset:3172
	s_nop 7
	ds_write_b32 v238, v202 offset:3176
	ds_write_b32 v238, v203 offset:3180
	s_nop 7
	ds_write_b32 v238, v204 offset:4224
	ds_write_b32 v238, v205 offset:4228
	s_nop 7
	ds_write_b32 v238, v206 offset:4232
	ds_write_b32 v238, v207 offset:4236
	s_nop 7
	ds_write_b32 v238, v208 offset:5280
	ds_write_b32 v238, v209 offset:5284
	s_nop 7
	ds_write_b32 v238, v210 offset:5288
	ds_write_b32 v238, v211 offset:5292
	s_nop 7
	ds_write_b32 v238, v212 offset:6336
	ds_write_b32 v238, v213 offset:6340
	s_nop 7
	ds_write_b32 v238, v214 offset:6344
	ds_write_b32 v238, v215 offset:6348
	s_nop 7
	ds_write_b32 v238, v216 offset:7392
	ds_write_b32 v238, v217 offset:7396
	s_nop 7
	ds_write_b32 v238, v218 offset:7400
	ds_write_b32 v238, v219 offset:7404
	s_nop 7
	s_waitcnt lgkmcnt(0)
	ds_read2_b32 v[148:149], v239 offset0:0 offset1:33
	s_nop 7
	ds_read2_b32 v[150:151], v239 offset0:66 offset1:99
	s_nop 7
	ds_read2_b32 v[152:153], v239 offset0:132 offset1:165
	s_nop 7
	ds_read2_b32 v[154:155], v239 offset0:198 offset1:231
	s_nop 7
	ds_read2_b32 v[156:157], v239 offset0:8 offset1:41
	s_nop 7
	ds_read2_b32 v[158:159], v239 offset0:74 offset1:107
	s_nop 7
	ds_read2_b32 v[160:161], v239 offset0:140 offset1:173
	s_nop 7
	ds_read2_b32 v[162:163], v239 offset0:206 offset1:239
	s_nop 7
	s_waitcnt lgkmcnt(4)
	v_cvt_pk_bf16_f32 v228, v148, v149
	v_cvt_pk_bf16_f32 v229, v150, v151
	v_cvt_pk_bf16_f32 v230, v152, v153
	v_cvt_pk_bf16_f32 v231, v154, v155
	global_store_dwordx4 v240, v[228:231], s[78:79] nt
	ds_read2_b32 v[148:149], v239 offset0:16 offset1:49
	s_nop 7
	ds_read2_b32 v[150:151], v239 offset0:82 offset1:115
	s_nop 7
	ds_read2_b32 v[152:153], v239 offset0:148 offset1:181
	s_nop 7
	ds_read2_b32 v[154:155], v239 offset0:214 offset1:247
	s_nop 7
	s_waitcnt lgkmcnt(4)
	v_cvt_pk_bf16_f32 v232, v156, v157
	v_cvt_pk_bf16_f32 v233, v158, v159
	v_cvt_pk_bf16_f32 v234, v160, v161
	v_cvt_pk_bf16_f32 v235, v162, v163
	s_mul_i32 s92, s81, 8
	s_add_u32 s94, s78, s92
	s_addc_u32 s95, s79, 0
	global_store_dwordx4 v240, v[232:235], s[94:95] nt
	ds_read2_b32 v[156:157], v239 offset0:24 offset1:57
	s_nop 7
	ds_read2_b32 v[158:159], v239 offset0:90 offset1:123
	s_nop 7
	ds_read2_b32 v[160:161], v239 offset0:156 offset1:189
	s_nop 7
	ds_read2_b32 v[162:163], v239 offset0:222 offset1:255
	s_nop 7
	s_waitcnt lgkmcnt(4)
	v_cvt_pk_bf16_f32 v228, v148, v149
	v_cvt_pk_bf16_f32 v229, v150, v151
	v_cvt_pk_bf16_f32 v230, v152, v153
	v_cvt_pk_bf16_f32 v231, v154, v155
	s_mul_i32 s92, s81, 16
	s_add_u32 s94, s78, s92
	s_addc_u32 s95, s79, 0
	global_store_dwordx4 v240, v[228:231], s[94:95] nt
	s_waitcnt lgkmcnt(0)
	v_cvt_pk_bf16_f32 v232, v156, v157
	v_cvt_pk_bf16_f32 v233, v158, v159
	v_cvt_pk_bf16_f32 v234, v160, v161
	v_cvt_pk_bf16_f32 v235, v162, v163
	s_mul_i32 s92, s81, 24
	s_add_u32 s94, s78, s92
	s_addc_u32 s95, s79, 0
	global_store_dwordx4 v240, v[232:235], s[94:95] nt
	s_mov_b32 s69, 0
